# GEMM K-loops: every 32-MFMA block starts on a 64-byte line (pad nops in the load sections)
# speedup vs baseline: 1.0041x; 1.0015x over previous
.LBB0_288:
	s_add_u32 s30, s28, 0xfffc0080
	s_addc_u32 s31, s29, -1
	s_add_i32 s56, 0, 0x10000
	s_cmp_eq_u32 s55, 12
	s_cselect_b32 s35, s21, s31
	s_cselect_b32 s34, s36, s30
	s_cselect_b32 s31, s19, s39
	s_cselect_b32 s30, s37, s38
	s_add_i32 s58, 0, 0x14000
	v_add_u32_e32 v166, s56, v147
	v_add_u32_e32 v182, s58, v147
	ds_read_b128 v[142:145], v166
	ds_read_b128 v[158:161], v166 offset:1024
	ds_read_b128 v[162:165], v166 offset:2048
	ds_read_b128 v[166:169], v166 offset:3072
	ds_read_b128 v[170:173], v182
	ds_read_b128 v[174:177], v182 offset:1024
	ds_read_b128 v[178:181], v182 offset:2048
	ds_read_b128 v[182:185], v182 offset:3072
	v_lshl_add_u64 v[224:225], s[28:29], 0, v[140:141]
	s_add_i32 m0, s44, 0xc000
	ds_read_b128 v[186:189], v157
	ds_read_b128 v[190:193], v157 offset:1024
	ds_read_b128 v[194:197], v157 offset:2048
	ds_read_b128 v[198:201], v157 offset:3072
	ds_read_b128 v[202:205], v157 offset:4096
	ds_read_b128 v[206:209], v157 offset:5120
	ds_read_b128 v[220:223], v157 offset:6144
	ds_read_b128 v[236:239], v157 offset:7168
	global_load_lds_dwordx4 v[224:225], off
	v_lshl_add_u64 v[224:225], s[28:29], 0, v[138:139]
	s_add_i32 m0, s44, 0xe000
	s_nop 0
	global_load_lds_dwordx4 v[224:225], off
	s_nop 0
	s_nop 0
	s_nop 0
	s_nop 0
	s_nop 0
	s_nop 0
	s_nop 0
	s_nop 0
	s_waitcnt vmcnt(8)
	s_waitcnt lgkmcnt(0)
	s_barrier
	s_waitcnt lgkmcnt(0)
	v_mfma_f32_16x16x32_bf16 v[126:129], v[142:145], v[186:189], v[126:129]
	v_mfma_f32_16x16x32_bf16 v[122:125], v[162:165], v[186:189], v[122:125]
	v_mfma_f32_16x16x32_bf16 v[110:113], v[142:145], v[194:197], v[110:113]
	v_mfma_f32_16x16x32_bf16 v[106:109], v[162:165], v[194:197], v[106:109]
	v_mfma_f32_16x16x32_bf16 v[94:97], v[142:145], v[202:205], v[94:97]
	v_mfma_f32_16x16x32_bf16 v[90:93], v[162:165], v[202:205], v[90:93]
	v_mfma_f32_16x16x32_bf16 v[78:81], v[142:145], v[220:223], v[78:81]
	v_mfma_f32_16x16x32_bf16 v[74:77], v[162:165], v[220:223], v[74:77]
	v_mfma_f32_16x16x32_bf16 v[126:129], v[158:161], v[190:193], v[126:129]
	v_mfma_f32_16x16x32_bf16 v[122:125], v[166:169], v[190:193], v[122:125]
	v_mfma_f32_16x16x32_bf16 v[110:113], v[158:161], v[198:201], v[110:113]
	v_mfma_f32_16x16x32_bf16 v[106:109], v[166:169], v[198:201], v[106:109]
	v_mfma_f32_16x16x32_bf16 v[94:97], v[158:161], v[206:209], v[94:97]
	v_mfma_f32_16x16x32_bf16 v[90:93], v[166:169], v[206:209], v[90:93]
	v_mfma_f32_16x16x32_bf16 v[78:81], v[158:161], v[236:239], v[78:81]
	v_mfma_f32_16x16x32_bf16 v[74:77], v[166:169], v[236:239], v[74:77]
	v_mfma_f32_16x16x32_bf16 v[118:121], v[170:173], v[186:189], v[118:121]
	v_mfma_f32_16x16x32_bf16 v[114:117], v[178:181], v[186:189], v[114:117]
	v_mfma_f32_16x16x32_bf16 v[102:105], v[170:173], v[194:197], v[102:105]
	v_mfma_f32_16x16x32_bf16 v[98:101], v[178:181], v[194:197], v[98:101]
	v_mfma_f32_16x16x32_bf16 v[86:89], v[170:173], v[202:205], v[86:89]
	v_mfma_f32_16x16x32_bf16 v[82:85], v[178:181], v[202:205], v[82:85]
	v_mfma_f32_16x16x32_bf16 v[70:73], v[170:173], v[220:223], v[70:73]
	v_mfma_f32_16x16x32_bf16 v[66:69], v[178:181], v[220:223], v[66:69]
	v_mfma_f32_16x16x32_bf16 v[118:121], v[174:177], v[190:193], v[118:121]
	v_mfma_f32_16x16x32_bf16 v[114:117], v[182:185], v[190:193], v[114:117]
	v_mfma_f32_16x16x32_bf16 v[102:105], v[174:177], v[198:201], v[102:105]
	v_mfma_f32_16x16x32_bf16 v[98:101], v[182:185], v[198:201], v[98:101]
	v_mfma_f32_16x16x32_bf16 v[86:89], v[174:177], v[206:209], v[86:89]
	v_mfma_f32_16x16x32_bf16 v[82:85], v[182:185], v[206:209], v[82:85]
	v_mfma_f32_16x16x32_bf16 v[70:73], v[174:177], v[236:239], v[70:73]
	v_mfma_f32_16x16x32_bf16 v[66:69], v[182:185], v[236:239], v[66:69]
	s_barrier
	s_add_i32 s56, s56, s27
	v_lshl_add_u64 v[224:225], s[30:31], 0, v[132:133]
	s_mov_b32 m0, s56
	ds_read_b128 v[186:189], v157 offset:16384
	ds_read_b128 v[190:193], v157 offset:17408
	ds_read_b128 v[194:197], v157 offset:18432
	ds_read_b128 v[198:201], v157 offset:19456
	ds_read_b128 v[202:205], v157 offset:20480
	ds_read_b128 v[206:209], v157 offset:21504
	ds_read_b128 v[220:223], v157 offset:22528
	ds_read_b128 v[236:239], v157 offset:23552
	global_load_lds_dwordx4 v[224:225], off
	s_add_i32 m0, s56, 0x2000
	s_add_u32 s56, s30, 0x40000
	v_lshl_add_u64 v[230:231], s[30:31], 0, v[136:137]
	s_addc_u32 s57, s31, 0
	s_add_i32 s58, s58, s27
	global_load_lds_dwordx4 v[230:231], off
	v_lshl_add_u64 v[240:241], s[56:57], 0, v[132:133]
	s_mov_b32 m0, s58
	v_lshl_add_u64 v[242:243], s[34:35], 0, v[134:135]
	global_load_lds_dwordx4 v[240:241], off
	v_lshl_add_u64 v[240:241], s[56:57], 0, v[136:137]
	s_add_i32 m0, s58, 0x2000
	s_nop 0
	global_load_lds_dwordx4 v[240:241], off
	v_lshl_add_u64 v[240:241], s[34:35], 0, v[130:131]
	s_mov_b32 m0, s44
	s_nop 0
	global_load_lds_dwordx4 v[240:241], off
	s_mov_b32 m0, s45
	s_nop 0
	global_load_lds_dwordx4 v[242:243], off
	s_nop 0
	s_nop 0
	s_nop 0
	s_waitcnt vmcnt(8)
	s_waitcnt lgkmcnt(0)
	s_barrier
	s_waitcnt lgkmcnt(0)
	v_mfma_f32_16x16x32_bf16 v[62:65], v[142:145], v[186:189], v[62:65]
	v_mfma_f32_16x16x32_bf16 v[58:61], v[162:165], v[186:189], v[58:61]
	v_mfma_f32_16x16x32_bf16 v[46:49], v[142:145], v[194:197], v[46:49]
	v_mfma_f32_16x16x32_bf16 v[42:45], v[162:165], v[194:197], v[42:45]
	v_mfma_f32_16x16x32_bf16 v[30:33], v[142:145], v[202:205], v[30:33]
	v_mfma_f32_16x16x32_bf16 v[26:29], v[162:165], v[202:205], v[26:29]
	v_mfma_f32_16x16x32_bf16 v[14:17], v[142:145], v[220:223], v[14:17]
	v_mfma_f32_16x16x32_bf16 v[10:13], v[162:165], v[220:223], v[10:13]
	v_mfma_f32_16x16x32_bf16 v[62:65], v[158:161], v[190:193], v[62:65]
	v_mfma_f32_16x16x32_bf16 v[58:61], v[166:169], v[190:193], v[58:61]
	v_mfma_f32_16x16x32_bf16 v[46:49], v[158:161], v[198:201], v[46:49]
	v_mfma_f32_16x16x32_bf16 v[42:45], v[166:169], v[198:201], v[42:45]
	v_mfma_f32_16x16x32_bf16 v[30:33], v[158:161], v[206:209], v[30:33]
	v_mfma_f32_16x16x32_bf16 v[26:29], v[166:169], v[206:209], v[26:29]
	v_mfma_f32_16x16x32_bf16 v[14:17], v[158:161], v[236:239], v[14:17]
	v_mfma_f32_16x16x32_bf16 v[10:13], v[166:169], v[236:239], v[10:13]
	v_mfma_f32_16x16x32_bf16 v[54:57], v[170:173], v[186:189], v[54:57]
	v_mfma_f32_16x16x32_bf16 v[50:53], v[178:181], v[186:189], v[50:53]
	v_mfma_f32_16x16x32_bf16 v[38:41], v[170:173], v[194:197], v[38:41]
	v_mfma_f32_16x16x32_bf16 v[34:37], v[178:181], v[194:197], v[34:37]
	v_mfma_f32_16x16x32_bf16 v[22:25], v[170:173], v[202:205], v[22:25]
	v_mfma_f32_16x16x32_bf16 v[18:21], v[178:181], v[202:205], v[18:21]
	v_mfma_f32_16x16x32_bf16 v[6:9], v[170:173], v[220:223], v[6:9]
	v_mfma_f32_16x16x32_bf16 v[2:5], v[178:181], v[220:223], v[2:5]
	v_mfma_f32_16x16x32_bf16 v[54:57], v[174:177], v[190:193], v[54:57]
	v_mfma_f32_16x16x32_bf16 v[50:53], v[182:185], v[190:193], v[50:53]
	v_mfma_f32_16x16x32_bf16 v[38:41], v[174:177], v[198:201], v[38:41]
	v_mfma_f32_16x16x32_bf16 v[34:37], v[182:185], v[198:201], v[34:37]
	v_mfma_f32_16x16x32_bf16 v[22:25], v[174:177], v[206:209], v[22:25]
	v_mfma_f32_16x16x32_bf16 v[18:21], v[182:185], v[206:209], v[18:21]
	v_mfma_f32_16x16x32_bf16 v[6:9], v[174:177], v[236:239], v[6:9]
	v_mfma_f32_16x16x32_bf16 v[2:5], v[182:185], v[236:239], v[2:5]
	s_barrier
	s_add_i32 s56, 0, 0x18000
	s_add_i32 s57, 0, 0x1c000
	v_add_u32_e32 v166, s56, v147
	v_add_u32_e32 v182, s57, v147
	ds_read_b128 v[142:145], v166
	ds_read_b128 v[158:161], v166 offset:1024
	ds_read_b128 v[162:165], v166 offset:2048
	ds_read_b128 v[166:169], v166 offset:3072
	ds_read_b128 v[170:173], v182
	ds_read_b128 v[174:177], v182 offset:1024
	ds_read_b128 v[178:181], v182 offset:2048
	ds_read_b128 v[182:185], v182 offset:3072
	s_add_u32 s34, s34, 0x40000
	s_addc_u32 s35, s35, 0
	s_mov_b32 m0, s43
	v_lshl_add_u64 v[244:245], s[34:35], 0, v[130:131]
	ds_read_b128 v[186:189], v157 offset:32768
	ds_read_b128 v[190:193], v157 offset:33792
	ds_read_b128 v[194:197], v157 offset:34816
	ds_read_b128 v[198:201], v157 offset:35840
	ds_read_b128 v[202:205], v157 offset:36864
	ds_read_b128 v[206:209], v157 offset:37888
	ds_read_b128 v[220:223], v157 offset:38912
	ds_read_b128 v[236:239], v157 offset:39936
	global_load_lds_dwordx4 v[244:245], off
	v_lshl_add_u64 v[244:245], s[34:35], 0, v[134:135]
	s_mov_b32 m0, s46
	s_nop 0
	global_load_lds_dwordx4 v[244:245], off
	s_nop 0
	s_nop 0
	s_nop 0
	s_nop 0
	s_nop 0
	s_nop 0
	s_nop 0
	s_waitcnt vmcnt(8)
	s_waitcnt lgkmcnt(0)
	s_barrier
	s_waitcnt lgkmcnt(0)
	v_mfma_f32_16x16x32_bf16 v[126:129], v[142:145], v[186:189], v[126:129]
	v_mfma_f32_16x16x32_bf16 v[122:125], v[162:165], v[186:189], v[122:125]
	v_mfma_f32_16x16x32_bf16 v[110:113], v[142:145], v[194:197], v[110:113]
	v_mfma_f32_16x16x32_bf16 v[106:109], v[162:165], v[194:197], v[106:109]
	v_mfma_f32_16x16x32_bf16 v[94:97], v[142:145], v[202:205], v[94:97]
	v_mfma_f32_16x16x32_bf16 v[90:93], v[162:165], v[202:205], v[90:93]
	v_mfma_f32_16x16x32_bf16 v[78:81], v[142:145], v[220:223], v[78:81]
	v_mfma_f32_16x16x32_bf16 v[74:77], v[162:165], v[220:223], v[74:77]
	v_mfma_f32_16x16x32_bf16 v[126:129], v[158:161], v[190:193], v[126:129]
	v_mfma_f32_16x16x32_bf16 v[122:125], v[166:169], v[190:193], v[122:125]
	v_mfma_f32_16x16x32_bf16 v[110:113], v[158:161], v[198:201], v[110:113]
	v_mfma_f32_16x16x32_bf16 v[106:109], v[166:169], v[198:201], v[106:109]
	v_mfma_f32_16x16x32_bf16 v[94:97], v[158:161], v[206:209], v[94:97]
	v_mfma_f32_16x16x32_bf16 v[90:93], v[166:169], v[206:209], v[90:93]
	v_mfma_f32_16x16x32_bf16 v[78:81], v[158:161], v[236:239], v[78:81]
	v_mfma_f32_16x16x32_bf16 v[74:77], v[166:169], v[236:239], v[74:77]
	v_mfma_f32_16x16x32_bf16 v[118:121], v[170:173], v[186:189], v[118:121]
	v_mfma_f32_16x16x32_bf16 v[114:117], v[178:181], v[186:189], v[114:117]
	v_mfma_f32_16x16x32_bf16 v[102:105], v[170:173], v[194:197], v[102:105]
	v_mfma_f32_16x16x32_bf16 v[98:101], v[178:181], v[194:197], v[98:101]
	v_mfma_f32_16x16x32_bf16 v[86:89], v[170:173], v[202:205], v[86:89]
	v_mfma_f32_16x16x32_bf16 v[82:85], v[178:181], v[202:205], v[82:85]
	v_mfma_f32_16x16x32_bf16 v[70:73], v[170:173], v[220:223], v[70:73]
	v_mfma_f32_16x16x32_bf16 v[66:69], v[178:181], v[220:223], v[66:69]
	v_mfma_f32_16x16x32_bf16 v[118:121], v[174:177], v[190:193], v[118:121]
	v_mfma_f32_16x16x32_bf16 v[114:117], v[182:185], v[190:193], v[114:117]
	v_mfma_f32_16x16x32_bf16 v[102:105], v[174:177], v[198:201], v[102:105]
	v_mfma_f32_16x16x32_bf16 v[98:101], v[182:185], v[198:201], v[98:101]
	v_mfma_f32_16x16x32_bf16 v[86:89], v[174:177], v[206:209], v[86:89]
	v_mfma_f32_16x16x32_bf16 v[82:85], v[182:185], v[206:209], v[82:85]
	v_mfma_f32_16x16x32_bf16 v[70:73], v[174:177], v[236:239], v[70:73]
	v_mfma_f32_16x16x32_bf16 v[66:69], v[182:185], v[236:239], v[66:69]
	s_barrier
	s_add_i32 s34, s56, s27
	v_lshl_add_u64 v[224:225], v[224:225], 0, s[96:97]
	s_mov_b32 m0, s34
	ds_read_b128 v[186:189], v157 offset:49152
	ds_read_b128 v[190:193], v157 offset:50176
	ds_read_b128 v[194:197], v157 offset:51200
	ds_read_b128 v[198:201], v157 offset:52224
	ds_read_b128 v[202:205], v157 offset:53248
	ds_read_b128 v[206:209], v157 offset:54272
	ds_read_b128 v[220:223], v157 offset:55296
	ds_read_b128 v[236:239], v157 offset:56320
	global_load_lds_dwordx4 v[224:225], off
	s_add_i32 m0, s34, 0x2000
	s_add_u32 s30, s30, 0x40080
	v_lshl_add_u64 v[224:225], v[230:231], 0, s[96:97]
	s_addc_u32 s31, s31, 0
	s_add_i32 s34, s57, s27
	global_load_lds_dwordx4 v[224:225], off
	v_lshl_add_u64 v[224:225], s[30:31], 0, v[132:133]
	s_mov_b32 m0, s34
	s_nop 0
	global_load_lds_dwordx4 v[224:225], off
	v_lshl_add_u64 v[224:225], s[30:31], 0, v[136:137]
	s_add_i32 m0, s34, 0x2000
	s_nop 0
	global_load_lds_dwordx4 v[224:225], off
	v_lshl_add_u64 v[224:225], v[240:241], 0, s[96:97]
	s_mov_b32 m0, s47
	s_nop 0
	global_load_lds_dwordx4 v[224:225], off
	v_lshl_add_u64 v[224:225], v[242:243], 0, s[96:97]
	s_mov_b32 m0, s48
	s_nop 0
	global_load_lds_dwordx4 v[224:225], off
	s_nop 0
	s_nop 0
	s_waitcnt vmcnt(8)
	s_waitcnt lgkmcnt(0)
	s_barrier
	s_waitcnt lgkmcnt(0)
	v_mfma_f32_16x16x32_bf16 v[62:65], v[142:145], v[186:189], v[62:65]
	v_mfma_f32_16x16x32_bf16 v[58:61], v[162:165], v[186:189], v[58:61]
	v_mfma_f32_16x16x32_bf16 v[46:49], v[142:145], v[194:197], v[46:49]
	v_mfma_f32_16x16x32_bf16 v[42:45], v[162:165], v[194:197], v[42:45]
	v_mfma_f32_16x16x32_bf16 v[30:33], v[142:145], v[202:205], v[30:33]
	v_mfma_f32_16x16x32_bf16 v[26:29], v[162:165], v[202:205], v[26:29]
	v_mfma_f32_16x16x32_bf16 v[14:17], v[142:145], v[220:223], v[14:17]
	v_mfma_f32_16x16x32_bf16 v[10:13], v[162:165], v[220:223], v[10:13]
	v_mfma_f32_16x16x32_bf16 v[62:65], v[158:161], v[190:193], v[62:65]
	v_mfma_f32_16x16x32_bf16 v[58:61], v[166:169], v[190:193], v[58:61]
	v_mfma_f32_16x16x32_bf16 v[46:49], v[158:161], v[198:201], v[46:49]
	v_mfma_f32_16x16x32_bf16 v[42:45], v[166:169], v[198:201], v[42:45]
	v_mfma_f32_16x16x32_bf16 v[30:33], v[158:161], v[206:209], v[30:33]
	v_mfma_f32_16x16x32_bf16 v[26:29], v[166:169], v[206:209], v[26:29]
	v_mfma_f32_16x16x32_bf16 v[14:17], v[158:161], v[236:239], v[14:17]
	v_mfma_f32_16x16x32_bf16 v[10:13], v[166:169], v[236:239], v[10:13]
	v_mfma_f32_16x16x32_bf16 v[54:57], v[170:173], v[186:189], v[54:57]
	v_mfma_f32_16x16x32_bf16 v[50:53], v[178:181], v[186:189], v[50:53]
	v_mfma_f32_16x16x32_bf16 v[38:41], v[170:173], v[194:197], v[38:41]
	v_mfma_f32_16x16x32_bf16 v[34:37], v[178:181], v[194:197], v[34:37]
	v_mfma_f32_16x16x32_bf16 v[22:25], v[170:173], v[202:205], v[22:25]
	v_mfma_f32_16x16x32_bf16 v[18:21], v[178:181], v[202:205], v[18:21]
	v_mfma_f32_16x16x32_bf16 v[6:9], v[170:173], v[220:223], v[6:9]
	v_mfma_f32_16x16x32_bf16 v[2:5], v[178:181], v[220:223], v[2:5]
	v_mfma_f32_16x16x32_bf16 v[54:57], v[174:177], v[190:193], v[54:57]
	v_mfma_f32_16x16x32_bf16 v[50:53], v[182:185], v[190:193], v[50:53]
	v_mfma_f32_16x16x32_bf16 v[38:41], v[174:177], v[198:201], v[38:41]
	v_mfma_f32_16x16x32_bf16 v[34:37], v[182:185], v[198:201], v[34:37]
	v_mfma_f32_16x16x32_bf16 v[22:25], v[174:177], v[206:209], v[22:25]
	v_mfma_f32_16x16x32_bf16 v[18:21], v[182:185], v[206:209], v[18:21]
	v_mfma_f32_16x16x32_bf16 v[6:9], v[174:177], v[236:239], v[6:9]
	v_mfma_f32_16x16x32_bf16 v[2:5], v[182:185], v[236:239], v[2:5]
	s_barrier
	s_add_i32 s55, s55, 2
	s_add_u32 s38, s38, 0x100
	s_addc_u32 s39, s39, 0
	s_add_u32 s28, s28, 0x100
	s_addc_u32 s29, s29, 0
	s_cmp_gt_u32 s55, 13
	s_cbranch_scc0 .LBB0_288
	s_and_b64 vcc, exec, s[12:13]
	s_cbranch_vccz .LBB0_291
	s_barrier

.LBB0_363:
	s_add_u32 s34, s30, 0xfffc0080
	s_addc_u32 s35, s31, -1
	s_add_i32 s57, 0, 0x10000
	s_cmp_eq_u32 s56, 12
	s_cselect_b32 s37, s23, s35
	s_cselect_b32 s36, s39, s34
	v_add_u32_e32 v146, s57, v155
	s_cselect_b32 s35, s21, s43
	s_cselect_b32 s34, s40, s41
	s_add_i32 s60, 0, 0x14000
	ds_read_b128 v[142:145], v146
	ds_read_b128 v[168:171], v146 offset:1024
	ds_read_b128 v[172:175], v146 offset:2048
	ds_read_b128 v[176:179], v146 offset:3072
	v_add_u32_e32 v146, s60, v155
	ds_read_b128 v[180:183], v146
	ds_read_b128 v[184:187], v146 offset:1024
	ds_read_b128 v[188:191], v146 offset:2048
	ds_read_b128 v[192:195], v146 offset:3072
	v_lshl_add_u64 v[146:147], s[30:31], 0, v[140:141]
	s_add_i32 m0, s48, 0xc000
	ds_read_b128 v[196:199], v157
	ds_read_b128 v[200:203], v157 offset:1024
	ds_read_b128 v[204:207], v157 offset:2048
	ds_read_b128 v[220:223], v157 offset:3072
	ds_read_b128 v[236:239], v157 offset:4096
	ds_read_b128 v[240:243], v157 offset:5120
	ds_read_b128 v[244:247], v157 offset:6144
	ds_read_b128 v[248:251], v157 offset:7168
	global_load_lds_dwordx4 v[146:147], off
	v_lshl_add_u64 v[146:147], s[30:31], 0, v[138:139]
	s_add_i32 m0, s48, 0xe000
	s_nop 0
	global_load_lds_dwordx4 v[146:147], off
	s_nop 0
	s_nop 0
	s_nop 0
	s_nop 0
	s_nop 0
	s_nop 0
	s_nop 0
	s_nop 0
	s_nop 0
	s_nop 0
	s_waitcnt vmcnt(8)
	s_waitcnt lgkmcnt(0)
	s_barrier
	s_waitcnt lgkmcnt(0)
	v_mfma_f32_16x16x32_bf16 v[126:129], v[142:145], v[196:199], v[126:129]
	v_mfma_f32_16x16x32_bf16 v[118:121], v[172:175], v[196:199], v[118:121]
	v_mfma_f32_16x16x32_bf16 v[110:113], v[142:145], v[204:207], v[110:113]
	v_mfma_f32_16x16x32_bf16 v[102:105], v[172:175], v[204:207], v[102:105]
	v_mfma_f32_16x16x32_bf16 v[94:97], v[142:145], v[236:239], v[94:97]
	v_mfma_f32_16x16x32_bf16 v[86:89], v[172:175], v[236:239], v[86:89]
	v_mfma_f32_16x16x32_bf16 v[78:81], v[142:145], v[244:247], v[78:81]
	v_mfma_f32_16x16x32_bf16 v[70:73], v[172:175], v[244:247], v[70:73]
	v_mfma_f32_16x16x32_bf16 v[126:129], v[168:171], v[200:203], v[126:129]
	v_mfma_f32_16x16x32_bf16 v[118:121], v[176:179], v[200:203], v[118:121]
	v_mfma_f32_16x16x32_bf16 v[110:113], v[168:171], v[220:223], v[110:113]
	v_mfma_f32_16x16x32_bf16 v[102:105], v[176:179], v[220:223], v[102:105]
	v_mfma_f32_16x16x32_bf16 v[94:97], v[168:171], v[240:243], v[94:97]
	v_mfma_f32_16x16x32_bf16 v[86:89], v[176:179], v[240:243], v[86:89]
	v_mfma_f32_16x16x32_bf16 v[78:81], v[168:171], v[248:251], v[78:81]
	v_mfma_f32_16x16x32_bf16 v[70:73], v[176:179], v[248:251], v[70:73]
	v_mfma_f32_16x16x32_bf16 v[122:125], v[180:183], v[196:199], v[122:125]
	v_mfma_f32_16x16x32_bf16 v[114:117], v[188:191], v[196:199], v[114:117]
	v_mfma_f32_16x16x32_bf16 v[106:109], v[180:183], v[204:207], v[106:109]
	v_mfma_f32_16x16x32_bf16 v[98:101], v[188:191], v[204:207], v[98:101]
	v_mfma_f32_16x16x32_bf16 v[90:93], v[180:183], v[236:239], v[90:93]
	v_mfma_f32_16x16x32_bf16 v[82:85], v[188:191], v[236:239], v[82:85]
	v_mfma_f32_16x16x32_bf16 v[74:77], v[180:183], v[244:247], v[74:77]
	v_mfma_f32_16x16x32_bf16 v[66:69], v[188:191], v[244:247], v[66:69]
	v_mfma_f32_16x16x32_bf16 v[122:125], v[184:187], v[200:203], v[122:125]
	v_mfma_f32_16x16x32_bf16 v[114:117], v[192:195], v[200:203], v[114:117]
	v_mfma_f32_16x16x32_bf16 v[106:109], v[184:187], v[220:223], v[106:109]
	v_mfma_f32_16x16x32_bf16 v[98:101], v[192:195], v[220:223], v[98:101]
	v_mfma_f32_16x16x32_bf16 v[90:93], v[184:187], v[240:243], v[90:93]
	v_mfma_f32_16x16x32_bf16 v[82:85], v[192:195], v[240:243], v[82:85]
	v_mfma_f32_16x16x32_bf16 v[74:77], v[184:187], v[248:251], v[74:77]
	v_mfma_f32_16x16x32_bf16 v[66:69], v[192:195], v[248:251], v[66:69]
	s_barrier
	s_add_i32 s57, s57, s44
	v_lshl_add_u64 v[146:147], s[34:35], 0, v[134:135]
	s_mov_b32 m0, s57
	ds_read_b128 v[196:199], v157 offset:16384
	ds_read_b128 v[200:203], v157 offset:17408
	ds_read_b128 v[204:207], v157 offset:18432
	ds_read_b128 v[220:223], v157 offset:19456
	ds_read_b128 v[236:239], v157 offset:20480
	ds_read_b128 v[240:243], v157 offset:21504
	ds_read_b128 v[244:247], v157 offset:22528
	ds_read_b128 v[248:251], v157 offset:23552
	global_load_lds_dwordx4 v[146:147], off
	s_add_i32 m0, s57, 0x2000
	s_add_u32 s58, s34, 0x40000
	v_lshl_add_u64 v[208:209], s[34:35], 0, v[130:131]
	s_addc_u32 s59, s35, 0
	s_add_i32 s57, s60, s44
	global_load_lds_dwordx4 v[208:209], off
	v_lshl_add_u64 v[224:225], s[58:59], 0, v[134:135]
	s_mov_b32 m0, s57
	v_lshl_add_u64 v[230:231], s[36:37], 0, v[132:133]
	global_load_lds_dwordx4 v[224:225], off
	v_lshl_add_u64 v[224:225], s[58:59], 0, v[130:131]
	s_add_i32 m0, s57, 0x2000
	s_nop 0
	global_load_lds_dwordx4 v[224:225], off
	v_lshl_add_u64 v[224:225], s[36:37], 0, v[136:137]
	s_mov_b32 m0, s48
	s_nop 0
	global_load_lds_dwordx4 v[224:225], off
	s_mov_b32 m0, s49
	s_nop 0
	global_load_lds_dwordx4 v[230:231], off
	s_nop 0
	s_nop 0
	s_nop 0
	s_waitcnt vmcnt(8)
	s_waitcnt lgkmcnt(0)
	s_barrier
	s_waitcnt lgkmcnt(0)
	v_mfma_f32_16x16x32_bf16 v[62:65], v[142:145], v[196:199], v[62:65]
	v_mfma_f32_16x16x32_bf16 v[54:57], v[172:175], v[196:199], v[54:57]
	v_mfma_f32_16x16x32_bf16 v[46:49], v[142:145], v[204:207], v[46:49]
	v_mfma_f32_16x16x32_bf16 v[38:41], v[172:175], v[204:207], v[38:41]
	v_mfma_f32_16x16x32_bf16 v[30:33], v[142:145], v[236:239], v[30:33]
	v_mfma_f32_16x16x32_bf16 v[22:25], v[172:175], v[236:239], v[22:25]
	v_mfma_f32_16x16x32_bf16 v[14:17], v[142:145], v[244:247], v[14:17]
	v_mfma_f32_16x16x32_bf16 v[6:9], v[172:175], v[244:247], v[6:9]
	v_mfma_f32_16x16x32_bf16 v[62:65], v[168:171], v[200:203], v[62:65]
	v_mfma_f32_16x16x32_bf16 v[54:57], v[176:179], v[200:203], v[54:57]
	v_mfma_f32_16x16x32_bf16 v[46:49], v[168:171], v[220:223], v[46:49]
	v_mfma_f32_16x16x32_bf16 v[38:41], v[176:179], v[220:223], v[38:41]
	v_mfma_f32_16x16x32_bf16 v[30:33], v[168:171], v[240:243], v[30:33]
	v_mfma_f32_16x16x32_bf16 v[22:25], v[176:179], v[240:243], v[22:25]
	v_mfma_f32_16x16x32_bf16 v[14:17], v[168:171], v[248:251], v[14:17]
	v_mfma_f32_16x16x32_bf16 v[6:9], v[176:179], v[248:251], v[6:9]
	v_mfma_f32_16x16x32_bf16 v[58:61], v[180:183], v[196:199], v[58:61]
	v_mfma_f32_16x16x32_bf16 v[50:53], v[188:191], v[196:199], v[50:53]
	v_mfma_f32_16x16x32_bf16 v[42:45], v[180:183], v[204:207], v[42:45]
	v_mfma_f32_16x16x32_bf16 v[34:37], v[188:191], v[204:207], v[34:37]
	v_mfma_f32_16x16x32_bf16 v[26:29], v[180:183], v[236:239], v[26:29]
	v_mfma_f32_16x16x32_bf16 v[18:21], v[188:191], v[236:239], v[18:21]
	v_mfma_f32_16x16x32_bf16 v[10:13], v[180:183], v[244:247], v[10:13]
	v_mfma_f32_16x16x32_bf16 v[2:5], v[188:191], v[244:247], v[2:5]
	v_mfma_f32_16x16x32_bf16 v[58:61], v[184:187], v[200:203], v[58:61]
	v_mfma_f32_16x16x32_bf16 v[50:53], v[192:195], v[200:203], v[50:53]
	v_mfma_f32_16x16x32_bf16 v[42:45], v[184:187], v[220:223], v[42:45]
	v_mfma_f32_16x16x32_bf16 v[34:37], v[192:195], v[220:223], v[34:37]
	v_mfma_f32_16x16x32_bf16 v[26:29], v[184:187], v[240:243], v[26:29]
	v_mfma_f32_16x16x32_bf16 v[18:21], v[192:195], v[240:243], v[18:21]
	v_mfma_f32_16x16x32_bf16 v[10:13], v[184:187], v[248:251], v[10:13]
	v_mfma_f32_16x16x32_bf16 v[2:5], v[192:195], v[248:251], v[2:5]
	s_barrier
	s_add_i32 s57, 0, 0x18000
	v_add_u32_e32 v164, s57, v155
	s_add_i32 s58, 0, 0x1c000
	ds_read_b128 v[142:145], v164
	ds_read_b128 v[168:171], v164 offset:1024
	ds_read_b128 v[172:175], v164 offset:2048
	ds_read_b128 v[176:179], v164 offset:3072
	v_add_u32_e32 v164, s58, v155
	ds_read_b128 v[180:183], v164
	ds_read_b128 v[184:187], v164 offset:1024
	ds_read_b128 v[188:191], v164 offset:2048
	ds_read_b128 v[192:195], v164 offset:3072
	s_add_u32 s36, s36, 0x40000
	s_addc_u32 s37, s37, 0
	s_mov_b32 m0, s50
	v_lshl_add_u64 v[252:253], s[36:37], 0, v[136:137]
	ds_read_b128 v[196:199], v157 offset:32768
	ds_read_b128 v[200:203], v157 offset:33792
	ds_read_b128 v[204:207], v157 offset:34816
	ds_read_b128 v[220:223], v157 offset:35840
	ds_read_b128 v[236:239], v157 offset:36864
	ds_read_b128 v[240:243], v157 offset:37888
	ds_read_b128 v[244:247], v157 offset:38912
	ds_read_b128 v[248:251], v157 offset:39936
	global_load_lds_dwordx4 v[252:253], off
	v_lshl_add_u64 v[252:253], s[36:37], 0, v[132:133]
	s_mov_b32 m0, s51
	s_nop 0
	global_load_lds_dwordx4 v[252:253], off
	s_nop 0
	s_nop 0
	s_nop 0
	s_nop 0
	s_nop 0
	s_nop 0
	s_nop 0
	s_waitcnt vmcnt(8)
	s_waitcnt lgkmcnt(0)
	s_barrier
	s_waitcnt lgkmcnt(0)
	v_mfma_f32_16x16x32_bf16 v[126:129], v[142:145], v[196:199], v[126:129]
	v_mfma_f32_16x16x32_bf16 v[118:121], v[172:175], v[196:199], v[118:121]
	v_mfma_f32_16x16x32_bf16 v[110:113], v[142:145], v[204:207], v[110:113]
	v_mfma_f32_16x16x32_bf16 v[102:105], v[172:175], v[204:207], v[102:105]
	v_mfma_f32_16x16x32_bf16 v[94:97], v[142:145], v[236:239], v[94:97]
	v_mfma_f32_16x16x32_bf16 v[86:89], v[172:175], v[236:239], v[86:89]
	v_mfma_f32_16x16x32_bf16 v[78:81], v[142:145], v[244:247], v[78:81]
	v_mfma_f32_16x16x32_bf16 v[70:73], v[172:175], v[244:247], v[70:73]
	v_mfma_f32_16x16x32_bf16 v[126:129], v[168:171], v[200:203], v[126:129]
	v_mfma_f32_16x16x32_bf16 v[118:121], v[176:179], v[200:203], v[118:121]
	v_mfma_f32_16x16x32_bf16 v[110:113], v[168:171], v[220:223], v[110:113]
	v_mfma_f32_16x16x32_bf16 v[102:105], v[176:179], v[220:223], v[102:105]
	v_mfma_f32_16x16x32_bf16 v[94:97], v[168:171], v[240:243], v[94:97]
	v_mfma_f32_16x16x32_bf16 v[86:89], v[176:179], v[240:243], v[86:89]
	v_mfma_f32_16x16x32_bf16 v[78:81], v[168:171], v[248:251], v[78:81]
	v_mfma_f32_16x16x32_bf16 v[70:73], v[176:179], v[248:251], v[70:73]
	v_mfma_f32_16x16x32_bf16 v[122:125], v[180:183], v[196:199], v[122:125]
	v_mfma_f32_16x16x32_bf16 v[114:117], v[188:191], v[196:199], v[114:117]
	v_mfma_f32_16x16x32_bf16 v[106:109], v[180:183], v[204:207], v[106:109]
	v_mfma_f32_16x16x32_bf16 v[98:101], v[188:191], v[204:207], v[98:101]
	v_mfma_f32_16x16x32_bf16 v[90:93], v[180:183], v[236:239], v[90:93]
	v_mfma_f32_16x16x32_bf16 v[82:85], v[188:191], v[236:239], v[82:85]
	v_mfma_f32_16x16x32_bf16 v[74:77], v[180:183], v[244:247], v[74:77]
	v_mfma_f32_16x16x32_bf16 v[66:69], v[188:191], v[244:247], v[66:69]
	v_mfma_f32_16x16x32_bf16 v[122:125], v[184:187], v[200:203], v[122:125]
	v_mfma_f32_16x16x32_bf16 v[114:117], v[192:195], v[200:203], v[114:117]
	v_mfma_f32_16x16x32_bf16 v[106:109], v[184:187], v[220:223], v[106:109]
	v_mfma_f32_16x16x32_bf16 v[98:101], v[192:195], v[220:223], v[98:101]
	v_mfma_f32_16x16x32_bf16 v[90:93], v[184:187], v[240:243], v[90:93]
	v_mfma_f32_16x16x32_bf16 v[82:85], v[192:195], v[240:243], v[82:85]
	v_mfma_f32_16x16x32_bf16 v[74:77], v[184:187], v[248:251], v[74:77]
	v_mfma_f32_16x16x32_bf16 v[66:69], v[192:195], v[248:251], v[66:69]
	s_barrier
	s_add_i32 s36, s57, s44
	v_lshl_add_u64 v[146:147], v[146:147], 0, s[96:97]
	s_mov_b32 m0, s36
	ds_read_b128 v[196:199], v157 offset:49152
	ds_read_b128 v[200:203], v157 offset:50176
	ds_read_b128 v[204:207], v157 offset:51200
	ds_read_b128 v[220:223], v157 offset:52224
	ds_read_b128 v[236:239], v157 offset:53248
	ds_read_b128 v[240:243], v157 offset:54272
	ds_read_b128 v[244:247], v157 offset:55296
	ds_read_b128 v[248:251], v157 offset:56320
	global_load_lds_dwordx4 v[146:147], off
	s_add_i32 m0, s36, 0x2000
	s_add_u32 s34, s34, 0x40080
	v_lshl_add_u64 v[146:147], v[208:209], 0, s[96:97]
	s_addc_u32 s35, s35, 0
	s_add_i32 s36, s58, s44
	global_load_lds_dwordx4 v[146:147], off
	v_lshl_add_u64 v[146:147], s[34:35], 0, v[134:135]
	s_mov_b32 m0, s36
	s_nop 0
	global_load_lds_dwordx4 v[146:147], off
	v_lshl_add_u64 v[146:147], s[34:35], 0, v[130:131]
	s_add_i32 m0, s36, 0x2000
	s_nop 0
	global_load_lds_dwordx4 v[146:147], off
	v_lshl_add_u64 v[146:147], v[224:225], 0, s[96:97]
	s_mov_b32 m0, s52
	s_nop 0
	global_load_lds_dwordx4 v[146:147], off
	v_lshl_add_u64 v[146:147], v[230:231], 0, s[96:97]
	s_mov_b32 m0, s53
	s_nop 0
	global_load_lds_dwordx4 v[146:147], off
	s_nop 0
	s_nop 0
	s_waitcnt vmcnt(8)
	s_waitcnt lgkmcnt(0)
	s_barrier
	s_waitcnt lgkmcnt(0)
	v_mfma_f32_16x16x32_bf16 v[62:65], v[142:145], v[196:199], v[62:65]
	v_mfma_f32_16x16x32_bf16 v[54:57], v[172:175], v[196:199], v[54:57]
	v_mfma_f32_16x16x32_bf16 v[46:49], v[142:145], v[204:207], v[46:49]
	v_mfma_f32_16x16x32_bf16 v[38:41], v[172:175], v[204:207], v[38:41]
	v_mfma_f32_16x16x32_bf16 v[30:33], v[142:145], v[236:239], v[30:33]
	v_mfma_f32_16x16x32_bf16 v[22:25], v[172:175], v[236:239], v[22:25]
	v_mfma_f32_16x16x32_bf16 v[14:17], v[142:145], v[244:247], v[14:17]
	v_mfma_f32_16x16x32_bf16 v[6:9], v[172:175], v[244:247], v[6:9]
	v_mfma_f32_16x16x32_bf16 v[62:65], v[168:171], v[200:203], v[62:65]
	v_mfma_f32_16x16x32_bf16 v[54:57], v[176:179], v[200:203], v[54:57]
	v_mfma_f32_16x16x32_bf16 v[46:49], v[168:171], v[220:223], v[46:49]
	v_mfma_f32_16x16x32_bf16 v[38:41], v[176:179], v[220:223], v[38:41]
	v_mfma_f32_16x16x32_bf16 v[30:33], v[168:171], v[240:243], v[30:33]
	v_mfma_f32_16x16x32_bf16 v[22:25], v[176:179], v[240:243], v[22:25]
	v_mfma_f32_16x16x32_bf16 v[14:17], v[168:171], v[248:251], v[14:17]
	v_mfma_f32_16x16x32_bf16 v[6:9], v[176:179], v[248:251], v[6:9]
	v_mfma_f32_16x16x32_bf16 v[58:61], v[180:183], v[196:199], v[58:61]
	v_mfma_f32_16x16x32_bf16 v[50:53], v[188:191], v[196:199], v[50:53]
	v_mfma_f32_16x16x32_bf16 v[42:45], v[180:183], v[204:207], v[42:45]
	v_mfma_f32_16x16x32_bf16 v[34:37], v[188:191], v[204:207], v[34:37]
	v_mfma_f32_16x16x32_bf16 v[26:29], v[180:183], v[236:239], v[26:29]
	v_mfma_f32_16x16x32_bf16 v[18:21], v[188:191], v[236:239], v[18:21]
	v_mfma_f32_16x16x32_bf16 v[10:13], v[180:183], v[244:247], v[10:13]
	v_mfma_f32_16x16x32_bf16 v[2:5], v[188:191], v[244:247], v[2:5]
	v_mfma_f32_16x16x32_bf16 v[58:61], v[184:187], v[200:203], v[58:61]
	v_mfma_f32_16x16x32_bf16 v[50:53], v[192:195], v[200:203], v[50:53]
	v_mfma_f32_16x16x32_bf16 v[42:45], v[184:187], v[220:223], v[42:45]
	v_mfma_f32_16x16x32_bf16 v[34:37], v[192:195], v[220:223], v[34:37]
	v_mfma_f32_16x16x32_bf16 v[26:29], v[184:187], v[240:243], v[26:29]
	v_mfma_f32_16x16x32_bf16 v[18:21], v[192:195], v[240:243], v[18:21]
	v_mfma_f32_16x16x32_bf16 v[10:13], v[184:187], v[248:251], v[10:13]
	v_mfma_f32_16x16x32_bf16 v[2:5], v[192:195], v[248:251], v[2:5]
	s_barrier
	s_add_i32 s56, s56, 2
	s_add_u32 s41, s41, 0x100
	s_addc_u32 s43, s43, 0
	s_add_u32 s30, s30, 0x100
	s_addc_u32 s31, s31, 0
	s_cmp_gt_u32 s56, 13
	s_cbranch_scc0 .LBB0_363
	s_and_b64 vcc, exec, s[16:17]
	s_cbranch_vccz .LBB0_366
	s_barrier

.LBB0_476:
	s_add_i32 s63, s31, 2
	s_add_u32 s38, s28, s36
	s_addc_u32 s39, s29, s37
	s_add_u32 s64, s26, s36
	s_addc_u32 s65, s27, s37
	s_add_i32 s66, 0, 0x10000
	s_cmp_eq_u32 s59, s31
	s_cselect_b32 s39, s9, s39
	s_cselect_b32 s38, s8, s38
	s_cselect_b32 s65, s35, s65
	s_cselect_b32 s64, s34, s64
	s_add_i32 s31, 0, 0x14000
	v_add_u32_e32 v160, s66, v146
	v_add_u32_e32 v176, s31, v146
	ds_read_b128 v[148:151], v160
	ds_read_b128 v[152:155], v160 offset:1024
	ds_read_b128 v[156:159], v160 offset:2048
	ds_read_b128 v[160:163], v160 offset:3072
	ds_read_b128 v[164:167], v176
	ds_read_b128 v[168:171], v176 offset:1024
	ds_read_b128 v[172:175], v176 offset:2048
	ds_read_b128 v[176:179], v176 offset:3072
	v_lshl_add_u64 v[208:209], s[28:29], 0, v[142:143]
	s_add_i32 m0, s51, 0xc000
	ds_read_b128 v[180:183], v147
	ds_read_b128 v[184:187], v147 offset:1024
	ds_read_b128 v[188:191], v147 offset:2048
	ds_read_b128 v[192:195], v147 offset:3072
	ds_read_b128 v[196:199], v147 offset:4096
	ds_read_b128 v[200:203], v147 offset:5120
	ds_read_b128 v[204:207], v147 offset:6144
	ds_read_b128 v[220:223], v147 offset:7168
	global_load_lds_dwordx4 v[208:209], off
	v_lshl_add_u64 v[208:209], s[28:29], 0, v[144:145]
	s_add_i32 m0, s51, 0xe000
	s_nop 0
	global_load_lds_dwordx4 v[208:209], off
	s_nop 0
	s_nop 0
	s_nop 0
	s_nop 0
	s_nop 0
	s_nop 0
	s_nop 0
	s_nop 0
	s_nop 0
	s_nop 0
	s_nop 0
	s_nop 0
	s_nop 0
	s_nop 0
	s_waitcnt vmcnt(8)
	s_waitcnt lgkmcnt(0)
	s_barrier
	s_waitcnt lgkmcnt(0)
	v_mfma_f32_16x16x32_bf16 v[126:129], v[148:151], v[180:183], v[126:129]
	v_mfma_f32_16x16x32_bf16 v[122:125], v[156:159], v[180:183], v[122:125]
	v_mfma_f32_16x16x32_bf16 v[110:113], v[148:151], v[188:191], v[110:113]
	v_mfma_f32_16x16x32_bf16 v[106:109], v[156:159], v[188:191], v[106:109]
	v_mfma_f32_16x16x32_bf16 v[94:97], v[148:151], v[196:199], v[94:97]
	v_mfma_f32_16x16x32_bf16 v[90:93], v[156:159], v[196:199], v[90:93]
	v_mfma_f32_16x16x32_bf16 v[78:81], v[148:151], v[204:207], v[78:81]
	v_mfma_f32_16x16x32_bf16 v[74:77], v[156:159], v[204:207], v[74:77]
	v_mfma_f32_16x16x32_bf16 v[126:129], v[152:155], v[184:187], v[126:129]
	v_mfma_f32_16x16x32_bf16 v[122:125], v[160:163], v[184:187], v[122:125]
	v_mfma_f32_16x16x32_bf16 v[110:113], v[152:155], v[192:195], v[110:113]
	v_mfma_f32_16x16x32_bf16 v[106:109], v[160:163], v[192:195], v[106:109]
	v_mfma_f32_16x16x32_bf16 v[94:97], v[152:155], v[200:203], v[94:97]
	v_mfma_f32_16x16x32_bf16 v[90:93], v[160:163], v[200:203], v[90:93]
	v_mfma_f32_16x16x32_bf16 v[78:81], v[152:155], v[220:223], v[78:81]
	v_mfma_f32_16x16x32_bf16 v[74:77], v[160:163], v[220:223], v[74:77]
	v_mfma_f32_16x16x32_bf16 v[118:121], v[164:167], v[180:183], v[118:121]
	v_mfma_f32_16x16x32_bf16 v[114:117], v[172:175], v[180:183], v[114:117]
	v_mfma_f32_16x16x32_bf16 v[102:105], v[164:167], v[188:191], v[102:105]
	v_mfma_f32_16x16x32_bf16 v[98:101], v[172:175], v[188:191], v[98:101]
	v_mfma_f32_16x16x32_bf16 v[86:89], v[164:167], v[196:199], v[86:89]
	v_mfma_f32_16x16x32_bf16 v[82:85], v[172:175], v[196:199], v[82:85]
	v_mfma_f32_16x16x32_bf16 v[70:73], v[164:167], v[204:207], v[70:73]
	v_mfma_f32_16x16x32_bf16 v[66:69], v[172:175], v[204:207], v[66:69]
	v_mfma_f32_16x16x32_bf16 v[118:121], v[168:171], v[184:187], v[118:121]
	v_mfma_f32_16x16x32_bf16 v[114:117], v[176:179], v[184:187], v[114:117]
	v_mfma_f32_16x16x32_bf16 v[102:105], v[168:171], v[192:195], v[102:105]
	v_mfma_f32_16x16x32_bf16 v[98:101], v[176:179], v[192:195], v[98:101]
	v_mfma_f32_16x16x32_bf16 v[86:89], v[168:171], v[200:203], v[86:89]
	v_mfma_f32_16x16x32_bf16 v[82:85], v[176:179], v[200:203], v[82:85]
	v_mfma_f32_16x16x32_bf16 v[70:73], v[168:171], v[220:223], v[70:73]
	v_mfma_f32_16x16x32_bf16 v[66:69], v[176:179], v[220:223], v[66:69]
	s_barrier
	s_add_i32 s66, s66, s47
	v_lshl_add_u64 v[208:209], s[64:65], 0, v[132:133]
	s_mov_b32 m0, s66
	ds_read_b128 v[180:183], v147 offset:16384
	ds_read_b128 v[184:187], v147 offset:17408
	ds_read_b128 v[188:191], v147 offset:18432
	ds_read_b128 v[192:195], v147 offset:19456
	ds_read_b128 v[196:199], v147 offset:20480
	ds_read_b128 v[200:203], v147 offset:21504
	ds_read_b128 v[204:207], v147 offset:22528
	ds_read_b128 v[220:223], v147 offset:23552
	global_load_lds_dwordx4 v[208:209], off
	s_add_i32 m0, s66, 0x2000
	v_lshl_add_u64 v[224:225], s[64:65], 0, v[136:137]
	s_add_u32 s64, s64, s45
	s_addc_u32 s65, s65, 0
	s_add_i32 s31, s31, s47
	global_load_lds_dwordx4 v[224:225], off
	v_lshl_add_u64 v[230:231], s[64:65], 0, v[132:133]
	s_mov_b32 m0, s31
	v_lshl_add_u64 v[236:237], s[64:65], 0, v[136:137]
	global_load_lds_dwordx4 v[230:231], off
	s_add_i32 m0, s31, 0x2000
	v_lshl_add_u64 v[238:239], s[38:39], 0, v[130:131]
	global_load_lds_dwordx4 v[236:237], off
	s_mov_b32 m0, s51
	v_lshl_add_u64 v[240:241], s[38:39], 0, v[134:135]
	global_load_lds_dwordx4 v[238:239], off
	s_mov_b32 m0, s52
	s_nop 0
	global_load_lds_dwordx4 v[240:241], off
	s_nop 0
	s_nop 0
	s_nop 0
	s_nop 0
	s_nop 0
	s_nop 0
	s_waitcnt vmcnt(8)
	s_waitcnt lgkmcnt(0)
	s_barrier
	s_waitcnt lgkmcnt(0)
	v_mfma_f32_16x16x32_bf16 v[62:65], v[148:151], v[180:183], v[62:65]
	v_mfma_f32_16x16x32_bf16 v[58:61], v[156:159], v[180:183], v[58:61]
	v_mfma_f32_16x16x32_bf16 v[46:49], v[148:151], v[188:191], v[46:49]
	v_mfma_f32_16x16x32_bf16 v[42:45], v[156:159], v[188:191], v[42:45]
	v_mfma_f32_16x16x32_bf16 v[30:33], v[148:151], v[196:199], v[30:33]
	v_mfma_f32_16x16x32_bf16 v[26:29], v[156:159], v[196:199], v[26:29]
	v_mfma_f32_16x16x32_bf16 v[14:17], v[148:151], v[204:207], v[14:17]
	v_mfma_f32_16x16x32_bf16 v[10:13], v[156:159], v[204:207], v[10:13]
	v_mfma_f32_16x16x32_bf16 v[62:65], v[152:155], v[184:187], v[62:65]
	v_mfma_f32_16x16x32_bf16 v[58:61], v[160:163], v[184:187], v[58:61]
	v_mfma_f32_16x16x32_bf16 v[46:49], v[152:155], v[192:195], v[46:49]
	v_mfma_f32_16x16x32_bf16 v[42:45], v[160:163], v[192:195], v[42:45]
	v_mfma_f32_16x16x32_bf16 v[30:33], v[152:155], v[200:203], v[30:33]
	v_mfma_f32_16x16x32_bf16 v[26:29], v[160:163], v[200:203], v[26:29]
	v_mfma_f32_16x16x32_bf16 v[14:17], v[152:155], v[220:223], v[14:17]
	v_mfma_f32_16x16x32_bf16 v[10:13], v[160:163], v[220:223], v[10:13]
	v_mfma_f32_16x16x32_bf16 v[54:57], v[164:167], v[180:183], v[54:57]
	v_mfma_f32_16x16x32_bf16 v[50:53], v[172:175], v[180:183], v[50:53]
	v_mfma_f32_16x16x32_bf16 v[38:41], v[164:167], v[188:191], v[38:41]
	v_mfma_f32_16x16x32_bf16 v[34:37], v[172:175], v[188:191], v[34:37]
	v_mfma_f32_16x16x32_bf16 v[22:25], v[164:167], v[196:199], v[22:25]
	v_mfma_f32_16x16x32_bf16 v[18:21], v[172:175], v[196:199], v[18:21]
	v_mfma_f32_16x16x32_bf16 v[6:9], v[164:167], v[204:207], v[6:9]
	v_mfma_f32_16x16x32_bf16 v[2:5], v[172:175], v[204:207], v[2:5]
	v_mfma_f32_16x16x32_bf16 v[54:57], v[168:171], v[184:187], v[54:57]
	v_mfma_f32_16x16x32_bf16 v[50:53], v[176:179], v[184:187], v[50:53]
	v_mfma_f32_16x16x32_bf16 v[38:41], v[168:171], v[192:195], v[38:41]
	v_mfma_f32_16x16x32_bf16 v[34:37], v[176:179], v[192:195], v[34:37]
	v_mfma_f32_16x16x32_bf16 v[22:25], v[168:171], v[200:203], v[22:25]
	v_mfma_f32_16x16x32_bf16 v[18:21], v[176:179], v[200:203], v[18:21]
	v_mfma_f32_16x16x32_bf16 v[6:9], v[168:171], v[220:223], v[6:9]
	v_mfma_f32_16x16x32_bf16 v[2:5], v[176:179], v[220:223], v[2:5]
	s_barrier
	s_add_i32 s31, 0, 0x18000
	s_add_i32 s64, 0, 0x1c000
	v_add_u32_e32 v160, s31, v146
	v_add_u32_e32 v176, s64, v146
	ds_read_b128 v[148:151], v160
	ds_read_b128 v[152:155], v160 offset:1024
	ds_read_b128 v[156:159], v160 offset:2048
	ds_read_b128 v[160:163], v160 offset:3072
	ds_read_b128 v[164:167], v176
	ds_read_b128 v[168:171], v176 offset:1024
	ds_read_b128 v[172:175], v176 offset:2048
	ds_read_b128 v[176:179], v176 offset:3072
	s_add_u32 s38, s38, s45
	s_addc_u32 s39, s39, 0
	s_mov_b32 m0, s53
	v_lshl_add_u64 v[242:243], s[38:39], 0, v[130:131]
	ds_read_b128 v[180:183], v147 offset:32768
	ds_read_b128 v[184:187], v147 offset:33792
	ds_read_b128 v[188:191], v147 offset:34816
	ds_read_b128 v[192:195], v147 offset:35840
	ds_read_b128 v[196:199], v147 offset:36864
	ds_read_b128 v[200:203], v147 offset:37888
	ds_read_b128 v[204:207], v147 offset:38912
	ds_read_b128 v[220:223], v147 offset:39936
	global_load_lds_dwordx4 v[242:243], off
	v_lshl_add_u64 v[242:243], s[38:39], 0, v[134:135]
	s_mov_b32 m0, s54
	s_nop 0
	global_load_lds_dwordx4 v[242:243], off
	s_nop 0
	s_nop 0
	s_nop 0
	s_nop 0
	s_nop 0
	s_nop 0
	s_nop 0
	s_nop 0
	s_waitcnt vmcnt(8)
	s_waitcnt lgkmcnt(0)
	s_barrier
	s_waitcnt lgkmcnt(0)
	v_mfma_f32_16x16x32_bf16 v[126:129], v[148:151], v[180:183], v[126:129]
	v_mfma_f32_16x16x32_bf16 v[122:125], v[156:159], v[180:183], v[122:125]
	v_mfma_f32_16x16x32_bf16 v[110:113], v[148:151], v[188:191], v[110:113]
	v_mfma_f32_16x16x32_bf16 v[106:109], v[156:159], v[188:191], v[106:109]
	v_mfma_f32_16x16x32_bf16 v[94:97], v[148:151], v[196:199], v[94:97]
	v_mfma_f32_16x16x32_bf16 v[90:93], v[156:159], v[196:199], v[90:93]
	v_mfma_f32_16x16x32_bf16 v[78:81], v[148:151], v[204:207], v[78:81]
	v_mfma_f32_16x16x32_bf16 v[74:77], v[156:159], v[204:207], v[74:77]
	v_mfma_f32_16x16x32_bf16 v[126:129], v[152:155], v[184:187], v[126:129]
	v_mfma_f32_16x16x32_bf16 v[122:125], v[160:163], v[184:187], v[122:125]
	v_mfma_f32_16x16x32_bf16 v[110:113], v[152:155], v[192:195], v[110:113]
	v_mfma_f32_16x16x32_bf16 v[106:109], v[160:163], v[192:195], v[106:109]
	v_mfma_f32_16x16x32_bf16 v[94:97], v[152:155], v[200:203], v[94:97]
	v_mfma_f32_16x16x32_bf16 v[90:93], v[160:163], v[200:203], v[90:93]
	v_mfma_f32_16x16x32_bf16 v[78:81], v[152:155], v[220:223], v[78:81]
	v_mfma_f32_16x16x32_bf16 v[74:77], v[160:163], v[220:223], v[74:77]
	v_mfma_f32_16x16x32_bf16 v[118:121], v[164:167], v[180:183], v[118:121]
	v_mfma_f32_16x16x32_bf16 v[114:117], v[172:175], v[180:183], v[114:117]
	v_mfma_f32_16x16x32_bf16 v[102:105], v[164:167], v[188:191], v[102:105]
	v_mfma_f32_16x16x32_bf16 v[98:101], v[172:175], v[188:191], v[98:101]
	v_mfma_f32_16x16x32_bf16 v[86:89], v[164:167], v[196:199], v[86:89]
	v_mfma_f32_16x16x32_bf16 v[82:85], v[172:175], v[196:199], v[82:85]
	v_mfma_f32_16x16x32_bf16 v[70:73], v[164:167], v[204:207], v[70:73]
	v_mfma_f32_16x16x32_bf16 v[66:69], v[172:175], v[204:207], v[66:69]
	v_mfma_f32_16x16x32_bf16 v[118:121], v[168:171], v[184:187], v[118:121]
	v_mfma_f32_16x16x32_bf16 v[114:117], v[176:179], v[184:187], v[114:117]
	v_mfma_f32_16x16x32_bf16 v[102:105], v[168:171], v[192:195], v[102:105]
	v_mfma_f32_16x16x32_bf16 v[98:101], v[176:179], v[192:195], v[98:101]
	v_mfma_f32_16x16x32_bf16 v[86:89], v[168:171], v[200:203], v[86:89]
	v_mfma_f32_16x16x32_bf16 v[82:85], v[176:179], v[200:203], v[82:85]
	v_mfma_f32_16x16x32_bf16 v[70:73], v[168:171], v[220:223], v[70:73]
	v_mfma_f32_16x16x32_bf16 v[66:69], v[176:179], v[220:223], v[66:69]
	s_barrier
	s_add_i32 s31, s31, s47
	v_lshl_add_u64 v[208:209], v[208:209], 0, s[96:97]
	s_mov_b32 m0, s31
	ds_read_b128 v[180:183], v147 offset:49152
	ds_read_b128 v[184:187], v147 offset:50176
	ds_read_b128 v[188:191], v147 offset:51200
	ds_read_b128 v[192:195], v147 offset:52224
	ds_read_b128 v[196:199], v147 offset:53248
	ds_read_b128 v[200:203], v147 offset:54272
	ds_read_b128 v[204:207], v147 offset:55296
	ds_read_b128 v[220:223], v147 offset:56320
	global_load_lds_dwordx4 v[208:209], off
	v_lshl_add_u64 v[208:209], v[224:225], 0, s[96:97]
	s_add_i32 m0, s31, 0x2000
	s_add_i32 s31, s64, s47
	global_load_lds_dwordx4 v[208:209], off
	v_lshl_add_u64 v[208:209], v[230:231], 0, s[96:97]
	s_mov_b32 m0, s31
	s_nop 0
	global_load_lds_dwordx4 v[208:209], off
	v_lshl_add_u64 v[208:209], v[236:237], 0, s[96:97]
	s_add_i32 m0, s31, 0x2000
	s_nop 0
	global_load_lds_dwordx4 v[208:209], off
	v_lshl_add_u64 v[208:209], v[238:239], 0, s[96:97]
	s_mov_b32 m0, s57
	s_nop 0
	global_load_lds_dwordx4 v[208:209], off
	v_lshl_add_u64 v[208:209], v[240:241], 0, s[96:97]
	s_mov_b32 m0, s58
	s_nop 0
	global_load_lds_dwordx4 v[208:209], off
	s_nop 0
	s_nop 0
	s_nop 0
	s_nop 0
	s_nop 0
	s_waitcnt vmcnt(8)
	s_waitcnt lgkmcnt(0)
	s_barrier
	s_waitcnt lgkmcnt(0)
	v_mfma_f32_16x16x32_bf16 v[62:65], v[148:151], v[180:183], v[62:65]
	v_mfma_f32_16x16x32_bf16 v[58:61], v[156:159], v[180:183], v[58:61]
	v_mfma_f32_16x16x32_bf16 v[46:49], v[148:151], v[188:191], v[46:49]
	v_mfma_f32_16x16x32_bf16 v[42:45], v[156:159], v[188:191], v[42:45]
	v_mfma_f32_16x16x32_bf16 v[30:33], v[148:151], v[196:199], v[30:33]
	v_mfma_f32_16x16x32_bf16 v[26:29], v[156:159], v[196:199], v[26:29]
	v_mfma_f32_16x16x32_bf16 v[14:17], v[148:151], v[204:207], v[14:17]
	v_mfma_f32_16x16x32_bf16 v[10:13], v[156:159], v[204:207], v[10:13]
	v_mfma_f32_16x16x32_bf16 v[62:65], v[152:155], v[184:187], v[62:65]
	v_mfma_f32_16x16x32_bf16 v[58:61], v[160:163], v[184:187], v[58:61]
	v_mfma_f32_16x16x32_bf16 v[46:49], v[152:155], v[192:195], v[46:49]
	v_mfma_f32_16x16x32_bf16 v[42:45], v[160:163], v[192:195], v[42:45]
	v_mfma_f32_16x16x32_bf16 v[30:33], v[152:155], v[200:203], v[30:33]
	v_mfma_f32_16x16x32_bf16 v[26:29], v[160:163], v[200:203], v[26:29]
	v_mfma_f32_16x16x32_bf16 v[14:17], v[152:155], v[220:223], v[14:17]
	v_mfma_f32_16x16x32_bf16 v[10:13], v[160:163], v[220:223], v[10:13]
	v_mfma_f32_16x16x32_bf16 v[54:57], v[164:167], v[180:183], v[54:57]
	v_mfma_f32_16x16x32_bf16 v[50:53], v[172:175], v[180:183], v[50:53]
	v_mfma_f32_16x16x32_bf16 v[38:41], v[164:167], v[188:191], v[38:41]
	v_mfma_f32_16x16x32_bf16 v[34:37], v[172:175], v[188:191], v[34:37]
	v_mfma_f32_16x16x32_bf16 v[22:25], v[164:167], v[196:199], v[22:25]
	v_mfma_f32_16x16x32_bf16 v[18:21], v[172:175], v[196:199], v[18:21]
	v_mfma_f32_16x16x32_bf16 v[6:9], v[164:167], v[204:207], v[6:9]
	v_mfma_f32_16x16x32_bf16 v[2:5], v[172:175], v[204:207], v[2:5]
	v_mfma_f32_16x16x32_bf16 v[54:57], v[168:171], v[184:187], v[54:57]
	v_mfma_f32_16x16x32_bf16 v[50:53], v[176:179], v[184:187], v[50:53]
	v_mfma_f32_16x16x32_bf16 v[38:41], v[168:171], v[192:195], v[38:41]
	v_mfma_f32_16x16x32_bf16 v[34:37], v[176:179], v[192:195], v[34:37]
	v_mfma_f32_16x16x32_bf16 v[22:25], v[168:171], v[200:203], v[22:25]
	v_mfma_f32_16x16x32_bf16 v[18:21], v[176:179], v[200:203], v[18:21]
	v_mfma_f32_16x16x32_bf16 v[6:9], v[168:171], v[220:223], v[6:9]
	v_mfma_f32_16x16x32_bf16 v[2:5], v[176:179], v[220:223], v[2:5]
	s_barrier
	s_add_u32 s36, s36, 0x100
	s_addc_u32 s37, s37, 0
	v_lshl_add_u64 v[144:145], v[144:145], 0, s[2:3]
	v_lshl_add_u64 v[142:143], v[142:143], 0, s[2:3]
	s_cmp_ge_u32 s63, s56
	s_mov_b32 s31, s63
	s_cbranch_scc0 .LBB0_476
	s_and_b64 vcc, exec, s[6:7]
	s_cbranch_vccnz .LBB0_464
	v_mov_b32_e32 v2, 0
	s_mov_b32 s55, s61
	s_mov_b32 s50, s62
	s_mov_b64 s[26:27], s[34:35]
	s_mov_b64 s[28:29], s[8:9]
	s_mov_b32 s60, s30
	v_mov_b32_e32 v3, v2
	v_mov_b32_e32 v4, v2
	v_mov_b32_e32 v5, v2
	v_mov_b32_e32 v6, v2
	v_mov_b32_e32 v7, v2
	v_mov_b32_e32 v8, v2
	v_mov_b32_e32 v9, v2
	v_mov_b32_e32 v18, v2
	v_mov_b32_e32 v19, v2
	v_mov_b32_e32 v20, v2
	v_mov_b32_e32 v21, v2
	v_mov_b32_e32 v22, v2
	v_mov_b32_e32 v23, v2
	v_mov_b32_e32 v24, v2
	v_mov_b32_e32 v25, v2
	v_mov_b32_e32 v34, v2
	v_mov_b32_e32 v35, v2
	v_mov_b32_e32 v36, v2
	v_mov_b32_e32 v37, v2
	v_mov_b32_e32 v38, v2
	v_mov_b32_e32 v39, v2
	v_mov_b32_e32 v40, v2
	v_mov_b32_e32 v41, v2
	v_mov_b32_e32 v50, v2
	v_mov_b32_e32 v51, v2
	v_mov_b32_e32 v52, v2
	v_mov_b32_e32 v53, v2
	v_mov_b32_e32 v54, v2
	v_mov_b32_e32 v55, v2
	v_mov_b32_e32 v56, v2
	v_mov_b32_e32 v57, v2
	v_mov_b32_e32 v10, v2
	v_mov_b32_e32 v11, v2
	v_mov_b32_e32 v12, v2
	v_mov_b32_e32 v13, v2
	v_mov_b32_e32 v14, v2
	v_mov_b32_e32 v15, v2
	v_mov_b32_e32 v16, v2
	v_mov_b32_e32 v17, v2
	v_mov_b32_e32 v26, v2
	v_mov_b32_e32 v27, v2
	v_mov_b32_e32 v28, v2
	v_mov_b32_e32 v29, v2
	v_mov_b32_e32 v30, v2
	v_mov_b32_e32 v31, v2
	v_mov_b32_e32 v32, v2
	v_mov_b32_e32 v33, v2
	v_mov_b32_e32 v42, v2
	v_mov_b32_e32 v43, v2
	v_mov_b32_e32 v44, v2
	v_mov_b32_e32 v45, v2
	v_mov_b32_e32 v46, v2
	v_mov_b32_e32 v47, v2
	v_mov_b32_e32 v48, v2
	v_mov_b32_e32 v49, v2
	v_mov_b32_e32 v58, v2
	v_mov_b32_e32 v59, v2
	v_mov_b32_e32 v60, v2
	v_mov_b32_e32 v61, v2
	v_mov_b32_e32 v62, v2
	v_mov_b32_e32 v63, v2
	v_mov_b32_e32 v64, v2
	v_mov_b32_e32 v65, v2
	v_mov_b32_e32 v66, v2
	v_mov_b32_e32 v67, v2
	v_mov_b32_e32 v68, v2
	v_mov_b32_e32 v69, v2
	v_mov_b32_e32 v70, v2
	v_mov_b32_e32 v71, v2
	v_mov_b32_e32 v72, v2
	v_mov_b32_e32 v73, v2
	v_mov_b32_e32 v82, v2
	v_mov_b32_e32 v83, v2
	v_mov_b32_e32 v84, v2
	v_mov_b32_e32 v85, v2
	v_mov_b32_e32 v86, v2
	v_mov_b32_e32 v87, v2
	v_mov_b32_e32 v88, v2
	v_mov_b32_e32 v89, v2
	v_mov_b32_e32 v98, v2
	v_mov_b32_e32 v99, v2
	v_mov_b32_e32 v100, v2
	v_mov_b32_e32 v101, v2
	v_mov_b32_e32 v102, v2
	v_mov_b32_e32 v103, v2
	v_mov_b32_e32 v104, v2
	v_mov_b32_e32 v105, v2
	v_mov_b32_e32 v114, v2
	v_mov_b32_e32 v115, v2
	v_mov_b32_e32 v116, v2
	v_mov_b32_e32 v117, v2
	v_mov_b32_e32 v118, v2
	v_mov_b32_e32 v119, v2
	v_mov_b32_e32 v120, v2
	v_mov_b32_e32 v121, v2
	v_mov_b32_e32 v74, v2
	v_mov_b32_e32 v75, v2
	v_mov_b32_e32 v76, v2
	v_mov_b32_e32 v77, v2
	v_mov_b32_e32 v78, v2
	v_mov_b32_e32 v79, v2
	v_mov_b32_e32 v80, v2
	v_mov_b32_e32 v81, v2
	v_mov_b32_e32 v90, v2
	v_mov_b32_e32 v91, v2
	v_mov_b32_e32 v92, v2
	v_mov_b32_e32 v93, v2
	v_mov_b32_e32 v94, v2
	v_mov_b32_e32 v95, v2
	v_mov_b32_e32 v96, v2
	v_mov_b32_e32 v97, v2
	v_mov_b32_e32 v106, v2
	v_mov_b32_e32 v107, v2
	v_mov_b32_e32 v108, v2
	v_mov_b32_e32 v109, v2
	v_mov_b32_e32 v110, v2
	v_mov_b32_e32 v111, v2
	v_mov_b32_e32 v112, v2
	v_mov_b32_e32 v113, v2
	v_mov_b32_e32 v122, v2
	v_mov_b32_e32 v123, v2
	v_mov_b32_e32 v124, v2
	v_mov_b32_e32 v125, v2
	v_mov_b32_e32 v126, v2
	v_mov_b32_e32 v127, v2
	v_mov_b32_e32 v128, v2
	v_mov_b32_e32 v129, v2
	s_branch .LBB0_464

.LBB0_640:
	s_add_u32 s22, s20, 0xfffc0080
	s_addc_u32 s23, s21, -1
	s_add_i32 s46, 0, 0x10000
	s_cmp_eq_u32 s45, 12
	s_cselect_b32 s25, s13, s23
	s_cselect_b32 s24, s19, s22
	v_add_u32_e32 v150, s46, v159
	s_cselect_b32 s23, s11, s44
	s_cselect_b32 s22, s41, s43
	s_add_i32 s48, 0, 0x14000
	ds_read_b128 v[164:167], v150
	ds_read_b128 v[168:171], v150 offset:1024
	ds_read_b128 v[172:175], v150 offset:2048
	ds_read_b128 v[176:179], v150 offset:3072
	v_add_u32_e32 v150, s48, v159
	ds_read_b128 v[180:183], v150
	ds_read_b128 v[184:187], v150 offset:1024
	ds_read_b128 v[188:191], v150 offset:2048
	ds_read_b128 v[192:195], v150 offset:3072
	v_lshl_add_u64 v[150:151], s[20:21], 0, v[140:141]
	s_add_i32 m0, s30, 0xc000
	ds_read_b128 v[196:199], v162
	ds_read_b128 v[200:203], v162 offset:1024
	ds_read_b128 v[204:207], v162 offset:2048
	ds_read_b128 v[220:223], v162 offset:3072
	ds_read_b128 v[236:239], v162 offset:4096
	ds_read_b128 v[240:243], v162 offset:5120
	ds_read_b128 v[244:247], v162 offset:6144
	ds_read_b128 v[248:251], v162 offset:7168
	global_load_lds_dwordx4 v[150:151], off
	v_lshl_add_u64 v[150:151], s[20:21], 0, v[138:139]
	s_add_i32 m0, s30, 0xe000
	s_nop 0
	global_load_lds_dwordx4 v[150:151], off
	s_nop 0
	s_nop 0
	s_nop 0
	s_nop 0
	s_nop 0
	s_nop 0
	s_nop 0
	s_nop 0
	s_nop 0
	s_nop 0
	s_nop 0
	s_nop 0
	s_nop 0
	s_waitcnt vmcnt(8)
	s_waitcnt lgkmcnt(0)
	s_barrier
	s_waitcnt lgkmcnt(0)
	v_mfma_f32_16x16x32_bf16 v[126:129], v[164:167], v[196:199], v[126:129]
	v_mfma_f32_16x16x32_bf16 v[122:125], v[172:175], v[196:199], v[122:125]
	v_mfma_f32_16x16x32_bf16 v[118:121], v[164:167], v[204:207], v[118:121]
	v_mfma_f32_16x16x32_bf16 v[114:117], v[172:175], v[204:207], v[114:117]
	v_mfma_f32_16x16x32_bf16 v[110:113], v[164:167], v[236:239], v[110:113]
	v_mfma_f32_16x16x32_bf16 v[106:109], v[172:175], v[236:239], v[106:109]
	v_mfma_f32_16x16x32_bf16 v[102:105], v[164:167], v[244:247], v[102:105]
	v_mfma_f32_16x16x32_bf16 v[98:101], v[172:175], v[244:247], v[98:101]
	v_mfma_f32_16x16x32_bf16 v[126:129], v[168:171], v[200:203], v[126:129]
	v_mfma_f32_16x16x32_bf16 v[122:125], v[176:179], v[200:203], v[122:125]
	v_mfma_f32_16x16x32_bf16 v[118:121], v[168:171], v[220:223], v[118:121]
	v_mfma_f32_16x16x32_bf16 v[114:117], v[176:179], v[220:223], v[114:117]
	v_mfma_f32_16x16x32_bf16 v[110:113], v[168:171], v[240:243], v[110:113]
	v_mfma_f32_16x16x32_bf16 v[106:109], v[176:179], v[240:243], v[106:109]
	v_mfma_f32_16x16x32_bf16 v[102:105], v[168:171], v[248:251], v[102:105]
	v_mfma_f32_16x16x32_bf16 v[98:101], v[176:179], v[248:251], v[98:101]
	v_mfma_f32_16x16x32_bf16 v[94:97], v[180:183], v[196:199], v[94:97]
	v_mfma_f32_16x16x32_bf16 v[90:93], v[188:191], v[196:199], v[90:93]
	v_mfma_f32_16x16x32_bf16 v[86:89], v[180:183], v[204:207], v[86:89]
	v_mfma_f32_16x16x32_bf16 v[82:85], v[188:191], v[204:207], v[82:85]
	v_mfma_f32_16x16x32_bf16 v[78:81], v[180:183], v[236:239], v[78:81]
	v_mfma_f32_16x16x32_bf16 v[74:77], v[188:191], v[236:239], v[74:77]
	v_mfma_f32_16x16x32_bf16 v[70:73], v[180:183], v[244:247], v[70:73]
	v_mfma_f32_16x16x32_bf16 v[66:69], v[188:191], v[244:247], v[66:69]
	v_mfma_f32_16x16x32_bf16 v[94:97], v[184:187], v[200:203], v[94:97]
	v_mfma_f32_16x16x32_bf16 v[90:93], v[192:195], v[200:203], v[90:93]
	v_mfma_f32_16x16x32_bf16 v[86:89], v[184:187], v[220:223], v[86:89]
	v_mfma_f32_16x16x32_bf16 v[82:85], v[192:195], v[220:223], v[82:85]
	v_mfma_f32_16x16x32_bf16 v[78:81], v[184:187], v[240:243], v[78:81]
	v_mfma_f32_16x16x32_bf16 v[74:77], v[192:195], v[240:243], v[74:77]
	v_mfma_f32_16x16x32_bf16 v[70:73], v[184:187], v[248:251], v[70:73]
	v_mfma_f32_16x16x32_bf16 v[66:69], v[192:195], v[248:251], v[66:69]
	s_barrier
	s_add_i32 s46, s46, s28
	v_lshl_add_u64 v[150:151], s[22:23], 0, v[134:135]
	s_mov_b32 m0, s46
	ds_read_b128 v[196:199], v162 offset:16384
	ds_read_b128 v[200:203], v162 offset:17408
	ds_read_b128 v[204:207], v162 offset:18432
	ds_read_b128 v[220:223], v162 offset:19456
	ds_read_b128 v[236:239], v162 offset:20480
	ds_read_b128 v[240:243], v162 offset:21504
	ds_read_b128 v[244:247], v162 offset:22528
	ds_read_b128 v[248:251], v162 offset:23552
	global_load_lds_dwordx4 v[150:151], off
	s_add_i32 m0, s46, 0x2000
	s_add_u32 s46, s22, 0x40000
	v_lshl_add_u64 v[208:209], s[22:23], 0, v[130:131]
	s_addc_u32 s47, s23, 0
	s_add_i32 s48, s48, s28
	global_load_lds_dwordx4 v[208:209], off
	v_lshl_add_u64 v[224:225], s[46:47], 0, v[134:135]
	s_mov_b32 m0, s48
	v_lshl_add_u64 v[252:253], s[24:25], 0, v[132:133]
	global_load_lds_dwordx4 v[224:225], off
	v_lshl_add_u64 v[224:225], s[46:47], 0, v[130:131]
	s_add_i32 m0, s48, 0x2000
	s_nop 0
	global_load_lds_dwordx4 v[224:225], off
	v_lshl_add_u64 v[224:225], s[24:25], 0, v[136:137]
	s_mov_b32 m0, s30
	s_nop 0
	global_load_lds_dwordx4 v[224:225], off
	s_mov_b32 m0, s31
	s_nop 0
	global_load_lds_dwordx4 v[252:253], off
	s_nop 0
	s_nop 0
	s_nop 0
	s_waitcnt vmcnt(8)
	s_waitcnt lgkmcnt(0)
	s_barrier
	s_waitcnt lgkmcnt(0)
	v_mfma_f32_16x16x32_bf16 v[62:65], v[164:167], v[196:199], v[62:65]
	v_mfma_f32_16x16x32_bf16 v[58:61], v[172:175], v[196:199], v[58:61]
	v_mfma_f32_16x16x32_bf16 v[54:57], v[164:167], v[204:207], v[54:57]
	v_mfma_f32_16x16x32_bf16 v[50:53], v[172:175], v[204:207], v[50:53]
	v_mfma_f32_16x16x32_bf16 v[46:49], v[164:167], v[236:239], v[46:49]
	v_mfma_f32_16x16x32_bf16 v[42:45], v[172:175], v[236:239], v[42:45]
	v_mfma_f32_16x16x32_bf16 v[38:41], v[164:167], v[244:247], v[38:41]
	v_mfma_f32_16x16x32_bf16 v[34:37], v[172:175], v[244:247], v[34:37]
	v_mfma_f32_16x16x32_bf16 v[62:65], v[168:171], v[200:203], v[62:65]
	v_mfma_f32_16x16x32_bf16 v[58:61], v[176:179], v[200:203], v[58:61]
	v_mfma_f32_16x16x32_bf16 v[54:57], v[168:171], v[220:223], v[54:57]
	v_mfma_f32_16x16x32_bf16 v[50:53], v[176:179], v[220:223], v[50:53]
	v_mfma_f32_16x16x32_bf16 v[46:49], v[168:171], v[240:243], v[46:49]
	v_mfma_f32_16x16x32_bf16 v[42:45], v[176:179], v[240:243], v[42:45]
	v_mfma_f32_16x16x32_bf16 v[38:41], v[168:171], v[248:251], v[38:41]
	v_mfma_f32_16x16x32_bf16 v[34:37], v[176:179], v[248:251], v[34:37]
	v_mfma_f32_16x16x32_bf16 v[30:33], v[180:183], v[196:199], v[30:33]
	v_mfma_f32_16x16x32_bf16 v[26:29], v[188:191], v[196:199], v[26:29]
	v_mfma_f32_16x16x32_bf16 v[22:25], v[180:183], v[204:207], v[22:25]
	v_mfma_f32_16x16x32_bf16 v[18:21], v[188:191], v[204:207], v[18:21]
	v_mfma_f32_16x16x32_bf16 v[14:17], v[180:183], v[236:239], v[14:17]
	v_mfma_f32_16x16x32_bf16 v[10:13], v[188:191], v[236:239], v[10:13]
	v_mfma_f32_16x16x32_bf16 v[6:9], v[180:183], v[244:247], v[6:9]
	v_mfma_f32_16x16x32_bf16 v[2:5], v[188:191], v[244:247], v[2:5]
	v_mfma_f32_16x16x32_bf16 v[30:33], v[184:187], v[200:203], v[30:33]
	v_mfma_f32_16x16x32_bf16 v[26:29], v[192:195], v[200:203], v[26:29]
	v_mfma_f32_16x16x32_bf16 v[22:25], v[184:187], v[220:223], v[22:25]
	v_mfma_f32_16x16x32_bf16 v[18:21], v[192:195], v[220:223], v[18:21]
	v_mfma_f32_16x16x32_bf16 v[14:17], v[184:187], v[240:243], v[14:17]
	v_mfma_f32_16x16x32_bf16 v[10:13], v[192:195], v[240:243], v[10:13]
	v_mfma_f32_16x16x32_bf16 v[6:9], v[184:187], v[248:251], v[6:9]
	v_mfma_f32_16x16x32_bf16 v[2:5], v[192:195], v[248:251], v[2:5]
	s_barrier
	s_add_i32 s46, 0, 0x18000
	v_add_u32_e32 v163, s46, v159
	s_add_i32 s47, 0, 0x1c000
	ds_read_b128 v[164:167], v163
	ds_read_b128 v[168:171], v163 offset:1024
	ds_read_b128 v[172:175], v163 offset:2048
	ds_read_b128 v[176:179], v163 offset:3072
	v_add_u32_e32 v163, s47, v159
	ds_read_b128 v[180:183], v163
	ds_read_b128 v[184:187], v163 offset:1024
	ds_read_b128 v[188:191], v163 offset:2048
	ds_read_b128 v[192:195], v163 offset:3072
	s_add_u32 s24, s24, 0x40000
	s_addc_u32 s25, s25, 0
	s_mov_b32 m0, s34
	v_lshl_add_u64 v[230:231], s[24:25], 0, v[136:137]
	ds_read_b128 v[196:199], v162 offset:32768
	ds_read_b128 v[200:203], v162 offset:33792
	ds_read_b128 v[204:207], v162 offset:34816
	ds_read_b128 v[220:223], v162 offset:35840
	ds_read_b128 v[236:239], v162 offset:36864
	ds_read_b128 v[240:243], v162 offset:37888
	ds_read_b128 v[244:247], v162 offset:38912
	ds_read_b128 v[248:251], v162 offset:39936
	global_load_lds_dwordx4 v[230:231], off
	v_lshl_add_u64 v[230:231], s[24:25], 0, v[132:133]
	s_mov_b32 m0, s35
	s_nop 0
	global_load_lds_dwordx4 v[230:231], off
	s_nop 0
	s_nop 0
	s_nop 0
	s_nop 0
	s_nop 0
	s_nop 0
	s_nop 0
	s_waitcnt vmcnt(8)
	s_waitcnt lgkmcnt(0)
	s_barrier
	s_waitcnt lgkmcnt(0)
	v_mfma_f32_16x16x32_bf16 v[126:129], v[164:167], v[196:199], v[126:129]
	v_mfma_f32_16x16x32_bf16 v[122:125], v[172:175], v[196:199], v[122:125]
	v_mfma_f32_16x16x32_bf16 v[118:121], v[164:167], v[204:207], v[118:121]
	v_mfma_f32_16x16x32_bf16 v[114:117], v[172:175], v[204:207], v[114:117]
	v_mfma_f32_16x16x32_bf16 v[110:113], v[164:167], v[236:239], v[110:113]
	v_mfma_f32_16x16x32_bf16 v[106:109], v[172:175], v[236:239], v[106:109]
	v_mfma_f32_16x16x32_bf16 v[102:105], v[164:167], v[244:247], v[102:105]
	v_mfma_f32_16x16x32_bf16 v[98:101], v[172:175], v[244:247], v[98:101]
	v_mfma_f32_16x16x32_bf16 v[126:129], v[168:171], v[200:203], v[126:129]
	v_mfma_f32_16x16x32_bf16 v[122:125], v[176:179], v[200:203], v[122:125]
	v_mfma_f32_16x16x32_bf16 v[118:121], v[168:171], v[220:223], v[118:121]
	v_mfma_f32_16x16x32_bf16 v[114:117], v[176:179], v[220:223], v[114:117]
	v_mfma_f32_16x16x32_bf16 v[110:113], v[168:171], v[240:243], v[110:113]
	v_mfma_f32_16x16x32_bf16 v[106:109], v[176:179], v[240:243], v[106:109]
	v_mfma_f32_16x16x32_bf16 v[102:105], v[168:171], v[248:251], v[102:105]
	v_mfma_f32_16x16x32_bf16 v[98:101], v[176:179], v[248:251], v[98:101]
	v_mfma_f32_16x16x32_bf16 v[94:97], v[180:183], v[196:199], v[94:97]
	v_mfma_f32_16x16x32_bf16 v[90:93], v[188:191], v[196:199], v[90:93]
	v_mfma_f32_16x16x32_bf16 v[86:89], v[180:183], v[204:207], v[86:89]
	v_mfma_f32_16x16x32_bf16 v[82:85], v[188:191], v[204:207], v[82:85]
	v_mfma_f32_16x16x32_bf16 v[78:81], v[180:183], v[236:239], v[78:81]
	v_mfma_f32_16x16x32_bf16 v[74:77], v[188:191], v[236:239], v[74:77]
	v_mfma_f32_16x16x32_bf16 v[70:73], v[180:183], v[244:247], v[70:73]
	v_mfma_f32_16x16x32_bf16 v[66:69], v[188:191], v[244:247], v[66:69]
	v_mfma_f32_16x16x32_bf16 v[94:97], v[184:187], v[200:203], v[94:97]
	v_mfma_f32_16x16x32_bf16 v[90:93], v[192:195], v[200:203], v[90:93]
	v_mfma_f32_16x16x32_bf16 v[86:89], v[184:187], v[220:223], v[86:89]
	v_mfma_f32_16x16x32_bf16 v[82:85], v[192:195], v[220:223], v[82:85]
	v_mfma_f32_16x16x32_bf16 v[78:81], v[184:187], v[240:243], v[78:81]
	v_mfma_f32_16x16x32_bf16 v[74:77], v[192:195], v[240:243], v[74:77]
	v_mfma_f32_16x16x32_bf16 v[70:73], v[184:187], v[248:251], v[70:73]
	v_mfma_f32_16x16x32_bf16 v[66:69], v[192:195], v[248:251], v[66:69]
	s_barrier
	s_add_i32 s24, s46, s28
	v_lshl_add_u64 v[150:151], v[150:151], 0, s[96:97]
	s_mov_b32 m0, s24
	ds_read_b128 v[196:199], v162 offset:49152
	ds_read_b128 v[200:203], v162 offset:50176
	ds_read_b128 v[204:207], v162 offset:51200
	ds_read_b128 v[220:223], v162 offset:52224
	ds_read_b128 v[236:239], v162 offset:53248
	ds_read_b128 v[240:243], v162 offset:54272
	ds_read_b128 v[244:247], v162 offset:55296
	ds_read_b128 v[248:251], v162 offset:56320
	global_load_lds_dwordx4 v[150:151], off
	s_add_i32 m0, s24, 0x2000
	s_add_u32 s22, s22, 0x40080
	v_lshl_add_u64 v[150:151], v[208:209], 0, s[96:97]
	s_addc_u32 s23, s23, 0
	s_add_i32 s24, s47, s28
	global_load_lds_dwordx4 v[150:151], off
	v_lshl_add_u64 v[150:151], s[22:23], 0, v[134:135]
	s_mov_b32 m0, s24
	s_nop 0
	global_load_lds_dwordx4 v[150:151], off
	v_lshl_add_u64 v[150:151], s[22:23], 0, v[130:131]
	s_add_i32 m0, s24, 0x2000
	s_nop 0
	global_load_lds_dwordx4 v[150:151], off
	v_lshl_add_u64 v[150:151], v[224:225], 0, s[96:97]
	s_mov_b32 m0, s36
	s_nop 0
	global_load_lds_dwordx4 v[150:151], off
	v_lshl_add_u64 v[150:151], v[252:253], 0, s[96:97]
	s_mov_b32 m0, s37
	s_nop 0
	global_load_lds_dwordx4 v[150:151], off
	s_nop 0
	s_nop 0
	s_waitcnt vmcnt(8)
	s_waitcnt lgkmcnt(0)
	s_barrier
	s_waitcnt lgkmcnt(0)
	v_mfma_f32_16x16x32_bf16 v[62:65], v[164:167], v[196:199], v[62:65]
	v_mfma_f32_16x16x32_bf16 v[58:61], v[172:175], v[196:199], v[58:61]
	v_mfma_f32_16x16x32_bf16 v[54:57], v[164:167], v[204:207], v[54:57]
	v_mfma_f32_16x16x32_bf16 v[50:53], v[172:175], v[204:207], v[50:53]
	v_mfma_f32_16x16x32_bf16 v[46:49], v[164:167], v[236:239], v[46:49]
	v_mfma_f32_16x16x32_bf16 v[42:45], v[172:175], v[236:239], v[42:45]
	v_mfma_f32_16x16x32_bf16 v[38:41], v[164:167], v[244:247], v[38:41]
	v_mfma_f32_16x16x32_bf16 v[34:37], v[172:175], v[244:247], v[34:37]
	v_mfma_f32_16x16x32_bf16 v[62:65], v[168:171], v[200:203], v[62:65]
	v_mfma_f32_16x16x32_bf16 v[58:61], v[176:179], v[200:203], v[58:61]
	v_mfma_f32_16x16x32_bf16 v[54:57], v[168:171], v[220:223], v[54:57]
	v_mfma_f32_16x16x32_bf16 v[50:53], v[176:179], v[220:223], v[50:53]
	v_mfma_f32_16x16x32_bf16 v[46:49], v[168:171], v[240:243], v[46:49]
	v_mfma_f32_16x16x32_bf16 v[42:45], v[176:179], v[240:243], v[42:45]
	v_mfma_f32_16x16x32_bf16 v[38:41], v[168:171], v[248:251], v[38:41]
	v_mfma_f32_16x16x32_bf16 v[34:37], v[176:179], v[248:251], v[34:37]
	v_mfma_f32_16x16x32_bf16 v[30:33], v[180:183], v[196:199], v[30:33]
	v_mfma_f32_16x16x32_bf16 v[26:29], v[188:191], v[196:199], v[26:29]
	v_mfma_f32_16x16x32_bf16 v[22:25], v[180:183], v[204:207], v[22:25]
	v_mfma_f32_16x16x32_bf16 v[18:21], v[188:191], v[204:207], v[18:21]
	v_mfma_f32_16x16x32_bf16 v[14:17], v[180:183], v[236:239], v[14:17]
	v_mfma_f32_16x16x32_bf16 v[10:13], v[188:191], v[236:239], v[10:13]
	v_mfma_f32_16x16x32_bf16 v[6:9], v[180:183], v[244:247], v[6:9]
	v_mfma_f32_16x16x32_bf16 v[2:5], v[188:191], v[244:247], v[2:5]
	v_mfma_f32_16x16x32_bf16 v[30:33], v[184:187], v[200:203], v[30:33]
	v_mfma_f32_16x16x32_bf16 v[26:29], v[192:195], v[200:203], v[26:29]
	v_mfma_f32_16x16x32_bf16 v[22:25], v[184:187], v[220:223], v[22:25]
	v_mfma_f32_16x16x32_bf16 v[18:21], v[192:195], v[220:223], v[18:21]
	v_mfma_f32_16x16x32_bf16 v[14:17], v[184:187], v[240:243], v[14:17]
	v_mfma_f32_16x16x32_bf16 v[10:13], v[192:195], v[240:243], v[10:13]
	v_mfma_f32_16x16x32_bf16 v[6:9], v[184:187], v[248:251], v[6:9]
	v_mfma_f32_16x16x32_bf16 v[2:5], v[192:195], v[248:251], v[2:5]
	s_barrier
	s_add_i32 s45, s45, 2
	s_add_u32 s43, s43, 0x100
	s_addc_u32 s44, s44, 0
	s_add_u32 s20, s20, 0x100
	s_addc_u32 s21, s21, 0
	s_cmp_gt_u32 s45, 13
	s_cbranch_scc0 .LBB0_640
	s_and_b64 vcc, exec, s[8:9]
	s_cbranch_vccz .LBB0_643
	s_barrier
